# PH8 epilogue: output store addresses via v_mad_u32_u24 + SGPR base (drops v_mad_i64_i32 and two 64-bit adds per store)
# baseline (speedup 1.0000x reference)
; #define SBAR() __builtin_amdgcn_sched_barrier(0)
; __device__ __forceinline__ float fast_sigmoid(float x) { return __builtin_amdgcn_rcpf(1.0f + __builtin_amdgcn_exp2f(-1.4426950408889634f * x)); }
; __device__ __forceinline__ u32x4 pack8(const f32x4 a, const f32x4 b) { u32x4 w; w.x = cvt_pk_bf16(a[0], a[1]); w.y = cvt_pk_bf16(a[2], a[3]); w.z = cvt_pk_bf16(b[0], b[1]); w.w = cvt_pk_bf16(b[2], b[3]); return w; }
;     __device__ __forceinline__ void operator()(f32x4 (&acc)[2][2][4][2], const Unit& u, int wr, int wc, int fr, int fq) const {
;     ...
;             float rsv[8];
; #pragma unroll
;             for (int i = 0; i < 8; ++i) rsv[i] = P.ssq_h1_()[ROWOF(i >> 2, i & 3)];
;             SBAR();
; #pragma unroll
;             for (int ai = 0; ai < 2; ++ai)
; #pragma unroll
;                 for (int m = 0; m < 4; ++m) { const int row = ROWOF(ai, m); const float rs = rsqrtf(rsv[ai * 4 + m] * (1.0f / 2048.0f) + EPS);
;                     f32x4 g0 = acc[ai][0][m][0] * rs, g1 = acc[ai][0][m][1] * rs; const f32x4 u0 = acc[ai][1][m][0] * rs, u1 = acc[ai][1][m][1] * rs;
; #pragma unroll
;                     for (int j = 0; j < 4; ++j) { g0[j] = g0[j] * fast_sigmoid(g0[j]) * u0[j]; g1[j] = g1[j] * fast_sigmoid(g1[j]) * u1[j]; }
;                     *(u32x4*)(P.f_() + (size_t)row * DFF + u.pn * 128 + c8) = pack8(g0, g1); }
.LBB0_1002:
	v_lshl_add_u32 v146, s22, 8, v150
	v_ashrrev_i32_e32 v147, 31, v146
	v_lshl_add_u64 v[156:157], v[146:147], 2, s[10:11]
	global_load_dword v158, v[156:157], off
	global_load_dword v159, v[156:157], off offset:64
	global_load_dword v164, v[156:157], off offset:128
	global_load_dword v165, v[156:157], off offset:192
	global_load_dword v166, v[156:157], off offset:512
	global_load_dword v149, v[156:157], off offset:576
	global_load_dword v148, v[156:157], off offset:640
	global_load_dword v147, v[156:157], off offset:704
	v_add_u32_e32 v156, 0x80, v146
	s_waitcnt vmcnt(0)
	v_fmamk_f32 v157, v158, 0x3a000000, v155
	v_mul_f32_e32 v158, 0x4b800000, v157
	v_cmp_gt_f32_e32 vcc, s51, v157
	s_lshl_b32 s22, s23, 7
	s_ashr_i32 s23, s22, 31
	v_cndmask_b32_e32 v157, v157, v158, vcc
	v_rsq_f32_e32 v157, v157
	s_lshl_b64 s[22:23], s[22:23], 1
	s_add_u32 s98, s12, s22
	s_addc_u32 s99, s13, s23
	v_mul_f32_e32 v158, 0x45800000, v157
	v_cndmask_b32_e32 v158, v157, v158, vcc
	v_pk_mul_f32 v[126:127], v[126:127], v[158:159] op_sel_hi:[1,0]
	v_pk_mul_f32 v[122:123], v[122:123], v[158:159] op_sel_hi:[1,0]
	v_mul_f32_e32 v157, 0xbfb8aa3b, v126
	v_mul_f32_e32 v160, 0xbfb8aa3b, v122
	v_exp_f32_e32 v157, v157
	v_exp_f32_e32 v161, v160
	v_mul_f32_e32 v160, 0xbfb8aa3b, v127
	v_exp_f32_e32 v162, v160
	v_add_f32_e32 v157, 1.0, v157
	v_rcp_f32_e32 v160, v157
	v_add_f32_e32 v157, 1.0, v161
	v_add_f32_e32 v161, 1.0, v162
	v_mul_f32_e32 v162, 0xbfb8aa3b, v123
	v_exp_f32_e32 v163, v162
	v_rcp_f32_e32 v161, v161
	v_rcp_f32_e32 v162, v157
	v_pk_mul_f32 v[128:129], v[128:129], v[158:159] op_sel_hi:[1,0]
	v_add_f32_e32 v157, 1.0, v163
	v_rcp_f32_e32 v163, v157
	v_pk_mul_f32 v[126:127], v[126:127], v[160:161]
	v_pk_mul_f32 v[118:119], v[118:119], v[158:159] op_sel_hi:[1,0]
	v_pk_mul_f32 v[124:125], v[124:125], v[158:159] op_sel_hi:[1,0]
	v_pk_mul_f32 v[118:119], v[118:119], v[126:127]
	v_mul_f32_e32 v126, 0xbfb8aa3b, v128
	v_pk_mul_f32 v[122:123], v[122:123], v[162:163]
	v_pk_mul_f32 v[114:115], v[114:115], v[158:159] op_sel_hi:[1,0]
	v_exp_f32_e32 v126, v126
	v_pk_mul_f32 v[114:115], v[114:115], v[122:123]
	v_mul_f32_e32 v123, 0xbfb8aa3b, v124
	v_exp_f32_e32 v123, v123
	v_add_f32_e32 v122, 1.0, v126
	v_mul_f32_e32 v126, 0xbfb8aa3b, v129
	v_exp_f32_e32 v126, v126
	v_add_f32_e32 v127, 1.0, v123
	v_mul_f32_e32 v123, 0xbfb8aa3b, v125
	v_exp_f32_e32 v157, v123
	v_add_f32_e32 v123, 1.0, v126
	v_rcp_f32_e32 v122, v122
	v_rcp_f32_e32 v123, v123
	v_rcp_f32_e32 v126, v127
	v_add_f32_e32 v127, 1.0, v157
	v_rcp_f32_e32 v127, v127
	v_pk_mul_f32 v[122:123], v[128:129], v[122:123]
	v_pk_mul_f32 v[120:121], v[120:121], v[158:159] op_sel_hi:[1,0]
	v_pk_mul_f32 v[116:117], v[116:117], v[158:159] op_sel_hi:[1,0]
	v_pk_mul_f32 v[120:121], v[120:121], v[122:123]
	v_pk_mul_f32 v[122:123], v[124:125], v[126:127]
	s_nop 0
	v_pk_mul_f32 v[122:123], v[116:117], v[122:123]
	v_cvt_pk_bf16_f32 v116, v118, v119
	v_cvt_pk_bf16_f32 v119, v122, v123
	v_fmamk_f32 v122, v159, 0x3a000000, v155
	v_mul_f32_e32 v123, 0x4b800000, v122
	v_cmp_gt_f32_e32 vcc, s51, v122
	v_cvt_pk_bf16_f32 v118, v114, v115
	v_cndmask_b32_e32 v122, v122, v123, vcc
	v_rsq_f32_e32 v122, v122
	v_cvt_pk_bf16_f32 v117, v120, v121
	v_mad_u32_u24 v120, v146, s52, v134
	global_store_dwordx4 v120, v[116:119], s[98:99]
	s_nop 1
	v_mul_f32_e32 v116, 0x45800000, v122
	v_cndmask_b32_e32 v116, v122, v116, vcc
	v_pk_mul_f32 v[110:111], v[110:111], v[116:117] op_sel_hi:[1,0]
	v_pk_mul_f32 v[106:107], v[106:107], v[116:117] op_sel_hi:[1,0]
	v_pk_mul_f32 v[112:113], v[112:113], v[116:117] op_sel_hi:[1,0]
	v_pk_mul_f32 v[108:109], v[108:109], v[116:117] op_sel_hi:[1,0]
	v_mul_f32_e32 v117, 0xbfb8aa3b, v110
	v_mul_f32_e32 v118, 0xbfb8aa3b, v106
	v_exp_f32_e32 v117, v117
	v_exp_f32_e32 v119, v118
	v_mul_f32_e32 v118, 0xbfb8aa3b, v111
	v_exp_f32_e32 v120, v118
	v_add_f32_e32 v117, 1.0, v117
	v_rcp_f32_e32 v118, v117
	v_add_f32_e32 v117, 1.0, v119
	v_add_f32_e32 v119, 1.0, v120
	v_mul_f32_e32 v120, 0xbfb8aa3b, v107
	v_exp_f32_e32 v121, v120
	v_rcp_f32_e32 v119, v119
	v_rcp_f32_e32 v120, v117
	v_pk_mul_f32 v[102:103], v[102:103], v[116:117] op_sel_hi:[1,0]
	v_add_f32_e32 v117, 1.0, v121
	v_rcp_f32_e32 v121, v117
	v_pk_mul_f32 v[110:111], v[110:111], v[118:119]
	v_pk_mul_f32 v[98:99], v[98:99], v[116:117] op_sel_hi:[1,0]
	v_pk_mul_f32 v[102:103], v[102:103], v[110:111]
	v_mul_f32_e32 v110, 0xbfb8aa3b, v112
	v_pk_mul_f32 v[106:107], v[106:107], v[120:121]
	v_exp_f32_e32 v110, v110
	v_pk_mul_f32 v[106:107], v[98:99], v[106:107]
	v_mul_f32_e32 v99, 0xbfb8aa3b, v108
	v_exp_f32_e32 v99, v99
	v_add_f32_e32 v98, 1.0, v110
	v_mul_f32_e32 v110, 0xbfb8aa3b, v113
	v_exp_f32_e32 v110, v110
	v_add_f32_e32 v111, 1.0, v99
	v_mul_f32_e32 v99, 0xbfb8aa3b, v109
	v_exp_f32_e32 v117, v99
	v_add_f32_e32 v99, 1.0, v110
	v_rcp_f32_e32 v98, v98
	v_rcp_f32_e32 v99, v99
	v_rcp_f32_e32 v110, v111
	v_add_f32_e32 v111, 1.0, v117
	v_rcp_f32_e32 v111, v111
	v_pk_mul_f32 v[98:99], v[112:113], v[98:99]
	v_pk_mul_f32 v[104:105], v[104:105], v[116:117] op_sel_hi:[1,0]
	v_pk_mul_f32 v[100:101], v[100:101], v[116:117] op_sel_hi:[1,0]
	v_pk_mul_f32 v[104:105], v[104:105], v[98:99]
	v_pk_mul_f32 v[98:99], v[108:109], v[110:111]
	v_or_b32_e32 v110, 16, v146
	v_pk_mul_f32 v[108:109], v[100:101], v[98:99]
	v_cvt_pk_bf16_f32 v99, v104, v105
	v_fmamk_f32 v104, v164, 0x3a000000, v155
	v_mul_f32_e32 v105, 0x4b800000, v104
	v_cmp_gt_f32_e32 vcc, s51, v104
	v_cvt_pk_bf16_f32 v98, v102, v103
	v_mad_u32_u24 v102, v110, s52, v134
	v_cndmask_b32_e32 v104, v104, v105, vcc
	v_rsq_f32_e32 v104, v104
	v_cvt_pk_bf16_f32 v100, v106, v107
	v_cvt_pk_bf16_f32 v101, v108, v109
	global_store_dwordx4 v102, v[98:101], s[98:99]
; __device__ __forceinline__ float fast_sigmoid(float x) { return __builtin_amdgcn_rcpf(1.0f + __builtin_amdgcn_exp2f(-1.4426950408889634f * x)); }
; __device__ __forceinline__ u32x4 pack8(const f32x4 a, const f32x4 b) { u32x4 w; w.x = cvt_pk_bf16(a[0], a[1]); w.y = cvt_pk_bf16(a[2], a[3]); w.z = cvt_pk_bf16(b[0], b[1]); w.w = cvt_pk_bf16(b[2], b[3]); return w; }
;     __device__ __forceinline__ void operator()(f32x4 (&acc)[2][2][4][2], const Unit& u, int wr, int wc, int fr, int fq) const {
;     ...
;                 for (int m = 0; m < 4; ++m) { const int row = ROWOF(ai, m); const float rs = rsqrtf(rsv[ai * 4 + m] * (1.0f / 2048.0f) + EPS);
;                     f32x4 g0 = acc[ai][0][m][0] * rs, g1 = acc[ai][0][m][1] * rs; const f32x4 u0 = acc[ai][1][m][0] * rs, u1 = acc[ai][1][m][1] * rs;
; #pragma unroll
;                     for (int j = 0; j < 4; ++j) { g0[j] = g0[j] * fast_sigmoid(g0[j]) * u0[j]; g1[j] = g1[j] * fast_sigmoid(g1[j]) * u1[j]; }
;                     *(u32x4*)(P.f_() + (size_t)row * DFF + u.pn * 128 + c8) = pack8(g0, g1); }
	s_nop 1
	v_mul_f32_e32 v98, 0x45800000, v104
	v_cndmask_b32_e32 v98, v104, v98, vcc
	v_pk_mul_f32 v[94:95], v[94:95], v[98:99] op_sel_hi:[1,0]
	v_pk_mul_f32 v[90:91], v[90:91], v[98:99] op_sel_hi:[1,0]
	v_pk_mul_f32 v[96:97], v[96:97], v[98:99] op_sel_hi:[1,0]
	v_pk_mul_f32 v[92:93], v[92:93], v[98:99] op_sel_hi:[1,0]
	v_mul_f32_e32 v99, 0xbfb8aa3b, v94
	v_mul_f32_e32 v100, 0xbfb8aa3b, v90
	v_exp_f32_e32 v99, v99
	v_exp_f32_e32 v101, v100
	v_mul_f32_e32 v100, 0xbfb8aa3b, v95
	v_exp_f32_e32 v102, v100
	v_add_f32_e32 v99, 1.0, v99
	v_rcp_f32_e32 v100, v99
	v_add_f32_e32 v99, 1.0, v101
	v_add_f32_e32 v101, 1.0, v102
	v_mul_f32_e32 v102, 0xbfb8aa3b, v91
	v_exp_f32_e32 v103, v102
	v_rcp_f32_e32 v101, v101
	v_rcp_f32_e32 v102, v99
	v_pk_mul_f32 v[86:87], v[86:87], v[98:99] op_sel_hi:[1,0]
	v_add_f32_e32 v99, 1.0, v103
	v_rcp_f32_e32 v103, v99
	v_pk_mul_f32 v[94:95], v[94:95], v[100:101]
	v_pk_mul_f32 v[82:83], v[82:83], v[98:99] op_sel_hi:[1,0]
	v_pk_mul_f32 v[86:87], v[86:87], v[94:95]
	v_mul_f32_e32 v94, 0xbfb8aa3b, v96
	v_pk_mul_f32 v[90:91], v[90:91], v[102:103]
	v_exp_f32_e32 v94, v94
	v_pk_mul_f32 v[90:91], v[82:83], v[90:91]
	v_mul_f32_e32 v83, 0xbfb8aa3b, v92
	v_exp_f32_e32 v83, v83
	v_add_f32_e32 v82, 1.0, v94
	v_mul_f32_e32 v94, 0xbfb8aa3b, v97
	v_exp_f32_e32 v94, v94
	v_add_f32_e32 v95, 1.0, v83
	v_mul_f32_e32 v83, 0xbfb8aa3b, v93
	v_exp_f32_e32 v99, v83
	v_add_f32_e32 v83, 1.0, v94
	v_rcp_f32_e32 v82, v82
	v_rcp_f32_e32 v83, v83
	v_rcp_f32_e32 v94, v95
	v_add_f32_e32 v95, 1.0, v99
	v_rcp_f32_e32 v95, v95
	v_pk_mul_f32 v[82:83], v[96:97], v[82:83]
	v_pk_mul_f32 v[88:89], v[88:89], v[98:99] op_sel_hi:[1,0]
	v_pk_mul_f32 v[84:85], v[84:85], v[98:99] op_sel_hi:[1,0]
	v_pk_mul_f32 v[88:89], v[88:89], v[82:83]
	v_pk_mul_f32 v[82:83], v[92:93], v[94:95]
	v_or_b32_e32 v94, 32, v146
	v_pk_mul_f32 v[92:93], v[84:85], v[82:83]
	v_cvt_pk_bf16_f32 v83, v88, v89
	v_fmamk_f32 v88, v165, 0x3a000000, v155
	v_mul_f32_e32 v89, 0x4b800000, v88
	v_cmp_gt_f32_e32 vcc, s51, v88
	v_cvt_pk_bf16_f32 v82, v86, v87
	v_mad_u32_u24 v86, v94, s52, v134
	v_cndmask_b32_e32 v88, v88, v89, vcc
	v_rsq_f32_e32 v88, v88
	v_cvt_pk_bf16_f32 v84, v90, v91
	v_cvt_pk_bf16_f32 v85, v92, v93
	global_store_dwordx4 v86, v[82:85], s[98:99]
	s_nop 1
	v_mul_f32_e32 v82, 0x45800000, v88
	v_cndmask_b32_e32 v82, v88, v82, vcc
	v_pk_mul_f32 v[78:79], v[78:79], v[82:83] op_sel_hi:[1,0]
	v_pk_mul_f32 v[74:75], v[74:75], v[82:83] op_sel_hi:[1,0]
	v_pk_mul_f32 v[80:81], v[80:81], v[82:83] op_sel_hi:[1,0]
	v_pk_mul_f32 v[76:77], v[76:77], v[82:83] op_sel_hi:[1,0]
	v_mul_f32_e32 v83, 0xbfb8aa3b, v78
	v_mul_f32_e32 v84, 0xbfb8aa3b, v74
	v_exp_f32_e32 v83, v83
	v_exp_f32_e32 v85, v84
	v_mul_f32_e32 v84, 0xbfb8aa3b, v79
	v_exp_f32_e32 v86, v84
	v_add_f32_e32 v83, 1.0, v83
	v_rcp_f32_e32 v84, v83
	v_add_f32_e32 v83, 1.0, v85
	v_add_f32_e32 v85, 1.0, v86
	v_mul_f32_e32 v86, 0xbfb8aa3b, v75
	v_exp_f32_e32 v87, v86
	v_rcp_f32_e32 v85, v85
	v_rcp_f32_e32 v86, v83
	v_pk_mul_f32 v[70:71], v[70:71], v[82:83] op_sel_hi:[1,0]
	v_add_f32_e32 v83, 1.0, v87
	v_rcp_f32_e32 v87, v83
	v_pk_mul_f32 v[78:79], v[78:79], v[84:85]
	v_pk_mul_f32 v[66:67], v[66:67], v[82:83] op_sel_hi:[1,0]
	v_pk_mul_f32 v[70:71], v[70:71], v[78:79]
	v_mul_f32_e32 v78, 0xbfb8aa3b, v80
	v_pk_mul_f32 v[74:75], v[74:75], v[86:87]
	v_exp_f32_e32 v78, v78
	v_pk_mul_f32 v[74:75], v[66:67], v[74:75]
	v_mul_f32_e32 v67, 0xbfb8aa3b, v76
	v_exp_f32_e32 v67, v67
	v_add_f32_e32 v66, 1.0, v78
	v_mul_f32_e32 v78, 0xbfb8aa3b, v81
	v_exp_f32_e32 v78, v78
	v_add_f32_e32 v79, 1.0, v67
	v_mul_f32_e32 v67, 0xbfb8aa3b, v77
	v_exp_f32_e32 v83, v67
	v_add_f32_e32 v67, 1.0, v78
	v_rcp_f32_e32 v66, v66
	v_rcp_f32_e32 v67, v67
	v_rcp_f32_e32 v78, v79
	v_add_f32_e32 v79, 1.0, v83
	v_rcp_f32_e32 v79, v79
	v_pk_mul_f32 v[66:67], v[80:81], v[66:67]
	v_pk_mul_f32 v[72:73], v[72:73], v[82:83] op_sel_hi:[1,0]
	v_pk_mul_f32 v[68:69], v[68:69], v[82:83] op_sel_hi:[1,0]
	v_pk_mul_f32 v[72:73], v[72:73], v[66:67]
	v_pk_mul_f32 v[66:67], v[76:77], v[78:79]
	v_or_b32_e32 v78, 48, v146
	v_pk_mul_f32 v[76:77], v[68:69], v[66:67]
	v_cvt_pk_bf16_f32 v67, v72, v73
	v_fmamk_f32 v72, v166, 0x3a000000, v155
	v_mul_f32_e32 v73, 0x4b800000, v72
	v_cmp_gt_f32_e32 vcc, s51, v72
	v_cvt_pk_bf16_f32 v66, v70, v71
	v_mad_u32_u24 v70, v78, s52, v134
	v_cndmask_b32_e32 v72, v72, v73, vcc
	v_rsq_f32_e32 v72, v72
	v_cvt_pk_bf16_f32 v68, v74, v75
	v_cvt_pk_bf16_f32 v69, v76, v77
	global_store_dwordx4 v70, v[66:69], s[98:99]
	s_nop 1
	v_mul_f32_e32 v66, 0x45800000, v72
	v_cndmask_b32_e32 v66, v72, v66, vcc
	v_pk_mul_f32 v[62:63], v[62:63], v[66:67] op_sel_hi:[1,0]
	v_pk_mul_f32 v[58:59], v[58:59], v[66:67] op_sel_hi:[1,0]
	v_pk_mul_f32 v[64:65], v[64:65], v[66:67] op_sel_hi:[1,0]
	v_pk_mul_f32 v[60:61], v[60:61], v[66:67] op_sel_hi:[1,0]
	v_mul_f32_e32 v67, 0xbfb8aa3b, v62
	v_mul_f32_e32 v68, 0xbfb8aa3b, v58
	v_exp_f32_e32 v67, v67
	v_exp_f32_e32 v69, v68
	v_mul_f32_e32 v68, 0xbfb8aa3b, v63
	v_exp_f32_e32 v70, v68
	v_add_f32_e32 v67, 1.0, v67
	v_rcp_f32_e32 v68, v67
	v_add_f32_e32 v67, 1.0, v69
	v_add_f32_e32 v69, 1.0, v70
	v_mul_f32_e32 v70, 0xbfb8aa3b, v59
	v_exp_f32_e32 v71, v70
	v_rcp_f32_e32 v69, v69
	v_rcp_f32_e32 v70, v67
	v_pk_mul_f32 v[54:55], v[54:55], v[66:67] op_sel_hi:[1,0]
	v_add_f32_e32 v67, 1.0, v71
	v_rcp_f32_e32 v71, v67
	v_pk_mul_f32 v[62:63], v[62:63], v[68:69]
	v_pk_mul_f32 v[50:51], v[50:51], v[66:67] op_sel_hi:[1,0]
	v_pk_mul_f32 v[54:55], v[54:55], v[62:63]
	v_mul_f32_e32 v62, 0xbfb8aa3b, v64
	v_pk_mul_f32 v[58:59], v[58:59], v[70:71]
	v_exp_f32_e32 v62, v62
	v_pk_mul_f32 v[58:59], v[50:51], v[58:59]
	v_mul_f32_e32 v51, 0xbfb8aa3b, v60
	v_exp_f32_e32 v51, v51
; __device__ __forceinline__ float fast_sigmoid(float x) { return __builtin_amdgcn_rcpf(1.0f + __builtin_amdgcn_exp2f(-1.4426950408889634f * x)); }
; __device__ __forceinline__ u32x4 pack8(const f32x4 a, const f32x4 b) { u32x4 w; w.x = cvt_pk_bf16(a[0], a[1]); w.y = cvt_pk_bf16(a[2], a[3]); w.z = cvt_pk_bf16(b[0], b[1]); w.w = cvt_pk_bf16(b[2], b[3]); return w; }
;     __device__ __forceinline__ void operator()(f32x4 (&acc)[2][2][4][2], const Unit& u, int wr, int wc, int fr, int fq) const {
;     ...
;                 for (int m = 0; m < 4; ++m) { const int row = ROWOF(ai, m); const float rs = rsqrtf(rsv[ai * 4 + m] * (1.0f / 2048.0f) + EPS);
;                     f32x4 g0 = acc[ai][0][m][0] * rs, g1 = acc[ai][0][m][1] * rs; const f32x4 u0 = acc[ai][1][m][0] * rs, u1 = acc[ai][1][m][1] * rs;
; #pragma unroll
;                     for (int j = 0; j < 4; ++j) { g0[j] = g0[j] * fast_sigmoid(g0[j]) * u0[j]; g1[j] = g1[j] * fast_sigmoid(g1[j]) * u1[j]; }
;                     *(u32x4*)(P.f_() + (size_t)row * DFF + u.pn * 128 + c8) = pack8(g0, g1); }
	v_add_f32_e32 v50, 1.0, v62
	v_mul_f32_e32 v62, 0xbfb8aa3b, v65
	v_exp_f32_e32 v62, v62
	v_add_f32_e32 v63, 1.0, v51
	v_mul_f32_e32 v51, 0xbfb8aa3b, v61
	v_exp_f32_e32 v67, v51
	v_add_f32_e32 v51, 1.0, v62
	v_rcp_f32_e32 v50, v50
	v_rcp_f32_e32 v51, v51
	v_rcp_f32_e32 v62, v63
	v_add_f32_e32 v63, 1.0, v67
	v_rcp_f32_e32 v63, v63
	v_pk_mul_f32 v[50:51], v[64:65], v[50:51]
	v_pk_mul_f32 v[56:57], v[56:57], v[66:67] op_sel_hi:[1,0]
	v_pk_mul_f32 v[52:53], v[52:53], v[66:67] op_sel_hi:[1,0]
	v_pk_mul_f32 v[56:57], v[56:57], v[50:51]
	v_pk_mul_f32 v[50:51], v[60:61], v[62:63]
	s_nop 0
	v_pk_mul_f32 v[60:61], v[52:53], v[50:51]
	v_cvt_pk_bf16_f32 v51, v56, v57
	v_fmamk_f32 v56, v149, 0x3a000000, v155
	v_mul_f32_e32 v57, 0x4b800000, v56
	v_cmp_gt_f32_e32 vcc, s51, v56
	v_cvt_pk_bf16_f32 v50, v54, v55
	v_mad_u32_u24 v54, v156, s52, v134
	v_cndmask_b32_e32 v56, v56, v57, vcc
	v_rsq_f32_e32 v56, v56
	v_cvt_pk_bf16_f32 v52, v58, v59
	v_cvt_pk_bf16_f32 v53, v60, v61
	global_store_dwordx4 v54, v[50:53], s[98:99]
	s_nop 1
	v_mul_f32_e32 v50, 0x45800000, v56
	v_cndmask_b32_e32 v50, v56, v50, vcc
	v_pk_mul_f32 v[46:47], v[46:47], v[50:51] op_sel_hi:[1,0]
	v_pk_mul_f32 v[42:43], v[42:43], v[50:51] op_sel_hi:[1,0]
	v_pk_mul_f32 v[48:49], v[48:49], v[50:51] op_sel_hi:[1,0]
	v_pk_mul_f32 v[44:45], v[44:45], v[50:51] op_sel_hi:[1,0]
	v_mul_f32_e32 v51, 0xbfb8aa3b, v46
	v_mul_f32_e32 v52, 0xbfb8aa3b, v42
	v_exp_f32_e32 v51, v51
	v_exp_f32_e32 v53, v52
	v_mul_f32_e32 v52, 0xbfb8aa3b, v47
	v_exp_f32_e32 v54, v52
	v_add_f32_e32 v51, 1.0, v51
	v_rcp_f32_e32 v52, v51
	v_add_f32_e32 v51, 1.0, v53
	v_add_f32_e32 v53, 1.0, v54
	v_mul_f32_e32 v54, 0xbfb8aa3b, v43
	v_exp_f32_e32 v55, v54
	v_rcp_f32_e32 v53, v53
	v_rcp_f32_e32 v54, v51
	v_pk_mul_f32 v[38:39], v[38:39], v[50:51] op_sel_hi:[1,0]
	v_add_f32_e32 v51, 1.0, v55
	v_rcp_f32_e32 v55, v51
	v_pk_mul_f32 v[46:47], v[46:47], v[52:53]
	v_pk_mul_f32 v[34:35], v[34:35], v[50:51] op_sel_hi:[1,0]
	v_pk_mul_f32 v[38:39], v[38:39], v[46:47]
	v_mul_f32_e32 v46, 0xbfb8aa3b, v48
	v_pk_mul_f32 v[42:43], v[42:43], v[54:55]
	v_exp_f32_e32 v46, v46
	v_pk_mul_f32 v[42:43], v[34:35], v[42:43]
	v_mul_f32_e32 v35, 0xbfb8aa3b, v44
	v_exp_f32_e32 v35, v35
	v_add_f32_e32 v34, 1.0, v46
	v_mul_f32_e32 v46, 0xbfb8aa3b, v49
	v_exp_f32_e32 v46, v46
	v_add_f32_e32 v47, 1.0, v35
	v_mul_f32_e32 v35, 0xbfb8aa3b, v45
	v_exp_f32_e32 v51, v35
	v_add_f32_e32 v35, 1.0, v46
	v_rcp_f32_e32 v34, v34
	v_rcp_f32_e32 v35, v35
	v_rcp_f32_e32 v46, v47
	v_add_f32_e32 v47, 1.0, v51
	v_rcp_f32_e32 v47, v47
	v_pk_mul_f32 v[34:35], v[48:49], v[34:35]
	v_pk_mul_f32 v[40:41], v[40:41], v[50:51] op_sel_hi:[1,0]
	v_pk_mul_f32 v[36:37], v[36:37], v[50:51] op_sel_hi:[1,0]
	v_pk_mul_f32 v[40:41], v[40:41], v[34:35]
	v_pk_mul_f32 v[34:35], v[44:45], v[46:47]
	v_add_u32_e32 v46, 0x90, v146
	v_pk_mul_f32 v[44:45], v[36:37], v[34:35]
	v_cvt_pk_bf16_f32 v35, v40, v41
	v_fmamk_f32 v40, v148, 0x3a000000, v155
	v_mul_f32_e32 v41, 0x4b800000, v40
	v_cmp_gt_f32_e32 vcc, s51, v40
	v_cvt_pk_bf16_f32 v34, v38, v39
	v_mad_u32_u24 v38, v46, s52, v134
	v_cndmask_b32_e32 v40, v40, v41, vcc
	v_rsq_f32_e32 v40, v40
	v_cvt_pk_bf16_f32 v36, v42, v43
	v_cvt_pk_bf16_f32 v37, v44, v45
	global_store_dwordx4 v38, v[34:37], s[98:99]
	s_nop 1
	v_mul_f32_e32 v34, 0x45800000, v40
	v_cndmask_b32_e32 v34, v40, v34, vcc
	v_pk_mul_f32 v[30:31], v[30:31], v[34:35] op_sel_hi:[1,0]
	v_pk_mul_f32 v[26:27], v[26:27], v[34:35] op_sel_hi:[1,0]
	v_pk_mul_f32 v[32:33], v[32:33], v[34:35] op_sel_hi:[1,0]
	v_pk_mul_f32 v[28:29], v[28:29], v[34:35] op_sel_hi:[1,0]
	v_mul_f32_e32 v35, 0xbfb8aa3b, v30
	v_mul_f32_e32 v36, 0xbfb8aa3b, v26
	v_exp_f32_e32 v35, v35
	v_exp_f32_e32 v37, v36
	v_mul_f32_e32 v36, 0xbfb8aa3b, v31
	v_exp_f32_e32 v38, v36
	v_add_f32_e32 v35, 1.0, v35
	v_rcp_f32_e32 v36, v35
	v_add_f32_e32 v35, 1.0, v37
; __device__ __forceinline__ float fast_sigmoid(float x) { return __builtin_amdgcn_rcpf(1.0f + __builtin_amdgcn_exp2f(-1.4426950408889634f * x)); }
; __device__ __forceinline__ u32x4 pack8(const f32x4 a, const f32x4 b) { u32x4 w; w.x = cvt_pk_bf16(a[0], a[1]); w.y = cvt_pk_bf16(a[2], a[3]); w.z = cvt_pk_bf16(b[0], b[1]); w.w = cvt_pk_bf16(b[2], b[3]); return w; }
; #define PG8_BAR __builtin_amdgcn_s_barrier()
; template <class Sched, class Epi>
; __device__ __forceinline__ void gemm_run(LAS unsigned char* lds, const Sched& S, const Epi& E) {
;     ...
;         if constexpr (!Epi::AFTER_DRAIN) E(acc, cur, wr, wc, fr, fq);
;         if (!has_next) break;
; #pragma unroll
;         for (int a = 0; a < 2; ++a)
; #pragma unroll
;             for (int b = 0; b < 2; ++b)
; #pragma unroll
;                 for (int m = 0; m < 4; ++m)
; #pragma unroll
;                     for (int n = 0; n < 2; ++n) acc[a][b][m][n] = (f32x4){0.f, 0.f, 0.f, 0.f};
;         cur = nxt; cA = nA; cB = nB; lda = nlda; ldb = nldb; ++ui;
;         if (wr == 1) PG8_BAR;
;     __device__ __forceinline__ void operator()(f32x4 (&acc)[2][2][4][2], const Unit& u, int wr, int wc, int fr, int fq) const {
;     ...
;                 for (int m = 0; m < 4; ++m) { const int row = ROWOF(ai, m); const float rs = rsqrtf(rsv[ai * 4 + m] * (1.0f / 2048.0f) + EPS);
;                     f32x4 g0 = acc[ai][0][m][0] * rs, g1 = acc[ai][0][m][1] * rs; const f32x4 u0 = acc[ai][1][m][0] * rs, u1 = acc[ai][1][m][1] * rs;
; #pragma unroll
;                     for (int j = 0; j < 4; ++j) { g0[j] = g0[j] * fast_sigmoid(g0[j]) * u0[j]; g1[j] = g1[j] * fast_sigmoid(g1[j]) * u1[j]; }
;                     *(u32x4*)(P.f_() + (size_t)row * DFF + u.pn * 128 + c8) = pack8(g0, g1); }
	v_add_f32_e32 v37, 1.0, v38
	v_mul_f32_e32 v38, 0xbfb8aa3b, v27
	v_exp_f32_e32 v39, v38
	v_rcp_f32_e32 v37, v37
	v_rcp_f32_e32 v38, v35
	v_pk_mul_f32 v[22:23], v[22:23], v[34:35] op_sel_hi:[1,0]
	v_add_f32_e32 v35, 1.0, v39
	v_rcp_f32_e32 v39, v35
	v_pk_mul_f32 v[30:31], v[30:31], v[36:37]
	v_pk_mul_f32 v[18:19], v[18:19], v[34:35] op_sel_hi:[1,0]
	v_pk_mul_f32 v[22:23], v[22:23], v[30:31]
	v_mul_f32_e32 v30, 0xbfb8aa3b, v32
	v_pk_mul_f32 v[26:27], v[26:27], v[38:39]
	v_exp_f32_e32 v30, v30
	v_pk_mul_f32 v[26:27], v[18:19], v[26:27]
	v_mul_f32_e32 v19, 0xbfb8aa3b, v28
	v_exp_f32_e32 v19, v19
	v_add_f32_e32 v18, 1.0, v30
	v_mul_f32_e32 v30, 0xbfb8aa3b, v33
	v_exp_f32_e32 v30, v30
	v_add_f32_e32 v31, 1.0, v19
	v_mul_f32_e32 v19, 0xbfb8aa3b, v29
	v_exp_f32_e32 v35, v19
	v_add_f32_e32 v19, 1.0, v30
	v_rcp_f32_e32 v18, v18
	v_rcp_f32_e32 v19, v19
	v_rcp_f32_e32 v30, v31
	v_add_f32_e32 v31, 1.0, v35
	v_rcp_f32_e32 v31, v31
	v_pk_mul_f32 v[18:19], v[32:33], v[18:19]
	v_pk_mul_f32 v[24:25], v[24:25], v[34:35] op_sel_hi:[1,0]
	v_pk_mul_f32 v[20:21], v[20:21], v[34:35] op_sel_hi:[1,0]
	v_pk_mul_f32 v[24:25], v[24:25], v[18:19]
	v_pk_mul_f32 v[18:19], v[28:29], v[30:31]
	v_add_u32_e32 v30, 0xa0, v146
	v_pk_mul_f32 v[28:29], v[20:21], v[18:19]
	v_cvt_pk_bf16_f32 v19, v24, v25
	v_fmamk_f32 v24, v147, 0x3a000000, v155
	v_mul_f32_e32 v25, 0x4b800000, v24
	v_cmp_gt_f32_e32 vcc, s51, v24
	v_cvt_pk_bf16_f32 v18, v22, v23
	v_mad_u32_u24 v22, v30, s52, v134
	v_cndmask_b32_e32 v24, v24, v25, vcc
	v_rsq_f32_e32 v24, v24
	v_cvt_pk_bf16_f32 v20, v26, v27
	v_cvt_pk_bf16_f32 v21, v28, v29
	global_store_dwordx4 v22, v[18:21], s[98:99]
	s_nop 1
	v_mul_f32_e32 v18, 0x45800000, v24
	v_cndmask_b32_e32 v18, v24, v18, vcc
	v_pk_mul_f32 v[14:15], v[14:15], v[18:19] op_sel_hi:[1,0]
	v_pk_mul_f32 v[10:11], v[10:11], v[18:19] op_sel_hi:[1,0]
	v_pk_mul_f32 v[16:17], v[16:17], v[18:19] op_sel_hi:[1,0]
	v_pk_mul_f32 v[12:13], v[12:13], v[18:19] op_sel_hi:[1,0]
	v_mul_f32_e32 v19, 0xbfb8aa3b, v14
	v_mul_f32_e32 v20, 0xbfb8aa3b, v10
	v_exp_f32_e32 v19, v19
	v_exp_f32_e32 v21, v20
	v_mul_f32_e32 v20, 0xbfb8aa3b, v15
	v_exp_f32_e32 v22, v20
	v_add_f32_e32 v19, 1.0, v19
	v_rcp_f32_e32 v20, v19
	v_add_f32_e32 v19, 1.0, v21
	v_add_f32_e32 v21, 1.0, v22
	v_mul_f32_e32 v22, 0xbfb8aa3b, v11
	v_exp_f32_e32 v23, v22
	v_rcp_f32_e32 v21, v21
	v_rcp_f32_e32 v22, v19
	v_pk_mul_f32 v[6:7], v[6:7], v[18:19] op_sel_hi:[1,0]
	v_add_f32_e32 v19, 1.0, v23
	v_rcp_f32_e32 v23, v19
	v_pk_mul_f32 v[14:15], v[14:15], v[20:21]
	v_pk_mul_f32 v[2:3], v[2:3], v[18:19] op_sel_hi:[1,0]
	v_pk_mul_f32 v[6:7], v[6:7], v[14:15]
	v_mul_f32_e32 v14, 0xbfb8aa3b, v16
	v_pk_mul_f32 v[10:11], v[10:11], v[22:23]
	v_exp_f32_e32 v14, v14
	v_pk_mul_f32 v[10:11], v[2:3], v[10:11]
	v_mul_f32_e32 v3, 0xbfb8aa3b, v12
	v_exp_f32_e32 v3, v3
	v_add_f32_e32 v2, 1.0, v14
	v_mul_f32_e32 v14, 0xbfb8aa3b, v17
	v_exp_f32_e32 v14, v14
	v_add_f32_e32 v15, 1.0, v3
	v_mul_f32_e32 v3, 0xbfb8aa3b, v13
	v_exp_f32_e32 v19, v3
	v_add_f32_e32 v3, 1.0, v14
	v_rcp_f32_e32 v2, v2
	v_rcp_f32_e32 v3, v3
	v_rcp_f32_e32 v14, v15
	v_add_f32_e32 v15, 1.0, v19
	v_rcp_f32_e32 v15, v15
	v_pk_mul_f32 v[2:3], v[16:17], v[2:3]
	v_pk_mul_f32 v[8:9], v[8:9], v[18:19] op_sel_hi:[1,0]
	v_pk_mul_f32 v[4:5], v[4:5], v[18:19] op_sel_hi:[1,0]
	v_pk_mul_f32 v[8:9], v[8:9], v[2:3]
	v_pk_mul_f32 v[2:3], v[12:13], v[14:15]
	v_add_u32_e32 v14, 0xb0, v146
	v_pk_mul_f32 v[12:13], v[4:5], v[2:3]
	v_cvt_pk_bf16_f32 v2, v6, v7
	v_mad_u32_u24 v6, v14, s52, v134
	v_cvt_pk_bf16_f32 v3, v8, v9
	v_cvt_pk_bf16_f32 v4, v10, v11
	v_cvt_pk_bf16_f32 v5, v12, v13
	s_andn2_b64 vcc, exec, s[18:19]
	s_mov_b64 s[18:19], -1
	global_store_dwordx4 v6, v[2:5], s[98:99]
	s_cbranch_vccnz .LBB0_995
	s_andn2_b64 vcc, exec, s[4:5]
	s_cbranch_vccnz .LBB0_994
	s_barrier
	s_branch .LBB0_994
